# phase 14 (final norm): g_final loaded once before the loop instead of one piece (plus vmcnt(0) drain incl. store acks) in front of each of the 16 stores per iteration
# speedup vs baseline: 1.0126x; 1.0126x over previous
.LBB0_1338:
	s_cmp_lt_i32 s74, 15
	s_cselect_b64 s[2:3], -1, 0
	s_and_b64 s[0:1], s[2:3], s[0:1]
	s_cmpk_lt_i32 s64, 0x2000
	s_cselect_b64 s[2:3], -1, 0
	s_and_b64 s[0:1], s[0:1], s[2:3]
	s_andn2_b64 vcc, exec, s[0:1]
	s_movk_i32 s15, 0x2000
	s_cbranch_vccnz .LBB0_1341
	s_lshl_b32 s2, s64, 2
	s_ashr_i32 s3, s2, 31
	s_lshl_b32 s4, s33, 5
	s_lshl_b64 s[0:1], s[2:3], 12
	s_add_u32 s0, s70, s0
	v_lshlrev_b32_e32 v32, 4, v181
	v_mov_b32_e32 v33, 0
	s_addc_u32 s1, s71, s1
	s_waitcnt vmcnt(0)
	v_lshl_add_u64 v[36:37], s[0:1], 0, v[32:33]
	s_lshl_b64 s[0:1], s[2:3], 11
	s_ashr_i32 s5, s4, 31
	v_lshl_or_b32 v38, v181, 3, s0
	s_mov_b32 s0, 0x358637bd
	v_lshl_add_u64 v[34:35], s[68:69], 0, v[32:33]
	global_load_dwordx4 v[120:123], v[34:35], off
	global_load_dwordx4 v[124:127], v[34:35], off offset:1024
	global_load_dwordx4 v[128:131], v[34:35], off offset:2048
	global_load_dwordx4 v[132:135], v[34:35], off offset:3072
	s_lshl_b64 s[6:7], s[4:5], 12
	v_mov_b32_e32 v39, s1
	s_lshl_b64 s[8:9], s[4:5], 11
	s_lshl_b64 s[10:11], s[2:3], 6
	s_lshl_b64 s[12:13], s[4:5], 6
	v_mov_b32_e32 v32, 0x2680000
	s_mov_b32 s14, 0x3a800000
	v_mov_b64_e32 v[40:41], s[0:1]
	s_mov_b32 s3, 0x800000
	s_mov_b32 s5, 0x13d01000
	s_movk_i32 s18, 0x1000
	s_movk_i32 s19, 0x3000
	s_waitcnt vmcnt(0)
.LBB0_1340:
	s_waitcnt lgkmcnt(0)
	v_lshl_add_u64 v[0:1], s[72:73], 0, v[38:39]
	s_add_u32 s16, s72, s10
	v_add_co_u32_e64 v10, s[0:1], s5, v0
	s_addc_u32 s17, s73, s11
	s_nop 0
	v_addc_co_u32_e64 v11, s[0:1], 0, v1, s[0:1]
	s_add_u32 s0, s16, 0x2680000
	v_add_co_u32_e32 v8, vcc, 0x13d00000, v0
	s_addc_u32 s1, s17, 0
	s_nop 1
	v_mov_b64_e32 v[58:59], v[120:121]
	v_mov_b64_e32 v[60:61], v[122:123]
	v_addc_co_u32_e32 v9, vcc, 0, v1, vcc
	global_load_dwordx4 v[62:65], v32, s[16:17]
	global_load_dwordx4 v[66:69], v32, s[16:17] offset:64
	global_load_dwordx2 v[56:57], v[10:11], off
	global_load_dwordx2 v[54:55], v[10:11], off offset:512
	global_load_dwordx2 v[52:53], v[10:11], off offset:1024
	global_load_dwordx2 v[50:51], v[10:11], off offset:1536
	global_load_dwordx2 v[48:49], v[10:11], off offset:2048
	global_load_dwordx2 v[46:47], v[10:11], off offset:2560
	global_load_dwordx2 v[44:45], v[10:11], off offset:3072
	global_load_dwordx2 v[42:43], v[10:11], off offset:3584
	global_load_dwordx4 v[4:7], v32, s[16:17] offset:128
	global_load_dwordx4 v[0:3], v32, s[16:17] offset:192
	global_load_dwordx4 v[70:73], v33, s[0:1] offset:48
	global_load_dwordx4 v[74:77], v33, s[0:1] offset:16
	global_load_dwordx4 v[78:81], v33, s[0:1] offset:32
	s_add_u32 s0, s16, 0x2680040
	s_addc_u32 s1, s17, 0
	global_load_dwordx4 v[82:85], v33, s[0:1] offset:16
	global_load_dwordx4 v[86:89], v33, s[0:1] offset:48
	global_load_dwordx4 v[90:93], v33, s[0:1] offset:32
	global_load_dwordx2 v[94:95], v[8:9], off
	global_load_dwordx2 v[96:97], v[8:9], off offset:512
	global_load_dwordx2 v[98:99], v[8:9], off offset:1024
	global_load_dwordx2 v[100:101], v[8:9], off offset:1536
	global_load_dwordx2 v[102:103], v[8:9], off offset:2048
	global_load_dwordx2 v[104:105], v[8:9], off offset:2560
	global_load_dwordx2 v[106:107], v[8:9], off offset:3072
	global_load_dwordx2 v[108:109], v[8:9], off offset:3584
	s_add_u32 s0, s16, 0x2680080
	s_addc_u32 s1, s17, 0
	global_load_dwordx4 v[20:23], v33, s[0:1] offset:48
	global_load_dwordx4 v[28:31], v33, s[0:1] offset:16
	global_load_dwordx4 v[24:27], v33, s[0:1] offset:32
	s_add_u32 s0, s16, 0x26800c0
	s_addc_u32 s1, s17, 0
	global_load_dwordx4 v[16:19], v33, s[0:1] offset:16
	global_load_dwordx4 v[8:11], v33, s[0:1] offset:48
	global_load_dwordx4 v[12:15], v33, s[0:1] offset:32
	s_add_i32 s2, s2, s4
	s_add_u32 s10, s10, s12
	s_addc_u32 s11, s11, s13
	v_lshl_add_u64 v[38:39], v[38:39], 0, s[8:9]
	s_cmp_lt_i32 s2, 0x8000
	s_waitcnt vmcnt(31)
	v_mov_b32_e32 v110, v62
	v_mov_b32_e32 v62, v64
	s_waitcnt vmcnt(30)
	v_mov_b32_e32 v64, v66
	v_mov_b32_e32 v66, v68
	s_waitcnt vmcnt(16)
	v_mov_b32_e32 v68, v82
	s_waitcnt vmcnt(13)
	v_lshlrev_b32_e32 v112, 16, v94
	v_and_b32_e32 v113, 0xffff0000, v94
	v_mov_b32_e32 v115, v70
	v_mov_b32_e32 v114, v74
	v_mov_b32_e32 v111, v78
	v_mov_b32_e32 v78, v63
	v_mov_b32_e32 v63, v80
	v_mov_b32_e32 v80, v65
	v_mov_b32_e32 v70, v75
	v_mov_b32_e32 v74, v76
	v_mov_b32_e32 v75, v72
	v_mov_b32_e32 v72, v77
	v_pk_add_f32 v[76:77], v[110:111], v[78:79]
	v_pk_add_f32 v[62:63], v[62:63], v[80:81]
	v_pk_add_f32 v[70:71], v[114:115], v[70:71]
	v_pk_add_f32 v[72:73], v[74:75], v[72:73]
	v_pk_add_f32 v[62:63], v[76:77], v[62:63]
	v_pk_add_f32 v[70:71], v[70:71], v[72:73]
	v_mov_b32_e32 v65, v90
	v_mov_b32_e32 v90, v67
	v_mov_b32_e32 v67, v92
	v_mov_b32_e32 v92, v69
	v_mov_b32_e32 v69, v86
	v_mov_b32_e32 v86, v83
	v_mov_b32_e32 v72, v84
	v_mov_b32_e32 v73, v88
	v_mov_b32_e32 v88, v85
	v_pk_add_f32 v[62:63], v[62:63], v[70:71]
	v_pk_add_f32 v[64:65], v[64:65], v[90:91]
	v_pk_add_f32 v[66:67], v[66:67], v[92:93]
	v_pk_add_f32 v[68:69], v[68:69], v[86:87]
	v_pk_add_f32 v[70:71], v[72:73], v[88:89]
	v_pk_add_f32 v[64:65], v[64:65], v[66:67]
	v_pk_add_f32 v[66:67], v[68:69], v[70:71]
	v_mov_b32_e32 v69, v62
	v_pk_add_f32 v[64:65], v[64:65], v[66:67]
	v_lshlrev_b32_e32 v94, 16, v95
	v_mov_b32_e32 v68, v64
	v_mov_b32_e32 v62, v65
	v_pk_add_f32 v[62:63], v[68:69], v[62:63]
	v_and_b32_e32 v95, 0xffff0000, v95
	v_pk_fma_f32 v[62:63], v[62:63], s[14:15], v[40:41] op_sel_hi:[1,0,0]
	s_waitcnt vmcnt(8)
	v_lshlrev_b32_e32 v70, 16, v105
	v_mul_f32_e32 v64, 0x4b800000, v63
	v_cmp_gt_f32_e32 vcc, s3, v63
	v_and_b32_e32 v71, 0xffff0000, v105
	s_nop 0
	v_cndmask_b32_e32 v63, v63, v64, vcc
	v_rsq_f32_e32 v63, v63
	s_nop 0
	v_mul_f32_e32 v64, 0x45800000, v63
	v_cndmask_b32_e32 v64, v63, v64, vcc
	v_pk_mul_f32 v[66:67], v[64:65], v[112:113] op_sel_hi:[0,1]
	v_pk_mul_f32 v[68:69], v[64:65], v[94:95] op_sel_hi:[0,1]
	v_pk_mul_f32 v[60:61], v[60:61], v[68:69]
	v_pk_mul_f32 v[58:59], v[58:59], v[66:67]
	global_store_dwordx4 v[36:37], v[58:61], off nt
	s_nop 1
	v_mov_b64_e32 v[58:59], v[124:125]
	v_mov_b64_e32 v[60:61], v[126:127]
	v_lshlrev_b32_e32 v66, 16, v96
	v_and_b32_e32 v67, 0xffff0000, v96
	v_lshlrev_b32_e32 v68, 16, v97
	v_and_b32_e32 v69, 0xffff0000, v97
	v_pk_mul_f32 v[68:69], v[64:65], v[68:69] op_sel_hi:[0,1]
	v_pk_mul_f32 v[66:67], v[64:65], v[66:67] op_sel_hi:[0,1]
	v_mul_f32_e32 v63, 0x4b800000, v62
	s_waitcnt vmcnt(1)
	v_pk_mul_f32 v[58:59], v[58:59], v[66:67]
	v_pk_mul_f32 v[60:61], v[60:61], v[68:69]
	global_store_dwordx4 v[36:37], v[58:61], off offset:1024 nt
	s_nop 1
	v_mov_b64_e32 v[58:59], v[128:129]
	v_mov_b64_e32 v[60:61], v[130:131]
	v_lshlrev_b32_e32 v66, 16, v98
	v_and_b32_e32 v67, 0xffff0000, v98
	v_lshlrev_b32_e32 v68, 16, v99
	v_and_b32_e32 v69, 0xffff0000, v99
	v_pk_mul_f32 v[68:69], v[64:65], v[68:69] op_sel_hi:[0,1]
	v_pk_mul_f32 v[66:67], v[64:65], v[66:67] op_sel_hi:[0,1]
	s_nop 0
	v_pk_mul_f32 v[58:59], v[58:59], v[66:67]
	v_pk_mul_f32 v[60:61], v[60:61], v[68:69]
	global_store_dwordx4 v[36:37], v[58:61], off offset:2048 nt
	s_nop 1
	v_mov_b64_e32 v[58:59], v[132:133]
	v_mov_b64_e32 v[60:61], v[134:135]
	v_lshlrev_b32_e32 v66, 16, v100
	v_and_b32_e32 v67, 0xffff0000, v100
	v_lshlrev_b32_e32 v68, 16, v101
	v_and_b32_e32 v69, 0xffff0000, v101
	v_pk_mul_f32 v[68:69], v[64:65], v[68:69] op_sel_hi:[0,1]
	v_pk_mul_f32 v[64:65], v[64:65], v[66:67] op_sel_hi:[0,1]
	v_lshlrev_b32_e32 v66, 16, v102
	v_and_b32_e32 v67, 0xffff0000, v102
	s_nop 0
	v_pk_mul_f32 v[58:59], v[58:59], v[64:65]
	v_pk_mul_f32 v[60:61], v[60:61], v[68:69]
	global_store_dwordx4 v[36:37], v[58:61], off offset:3072 nt
	s_nop 1
	v_mov_b64_e32 v[58:59], v[120:121]
	v_mov_b64_e32 v[60:61], v[122:123]
	v_add_co_u32_e32 v64, vcc, s15, v36
	v_lshlrev_b32_e32 v68, 16, v103
	s_nop 0
	v_addc_co_u32_e32 v65, vcc, 0, v37, vcc
	v_cmp_gt_f32_e32 vcc, s3, v62
	v_and_b32_e32 v69, 0xffff0000, v103
	s_nop 0
	v_cndmask_b32_e32 v62, v62, v63, vcc
	v_rsq_f32_e32 v62, v62
	s_nop 0
	v_mul_f32_e32 v63, 0x45800000, v62
	v_cndmask_b32_e32 v62, v62, v63, vcc
	v_pk_mul_f32 v[68:69], v[62:63], v[68:69] op_sel_hi:[0,1]
	v_pk_mul_f32 v[66:67], v[62:63], v[66:67] op_sel_hi:[0,1]
	v_pk_mul_f32 v[70:71], v[62:63], v[70:71] op_sel_hi:[0,1]
	s_nop 0
	v_pk_mul_f32 v[58:59], v[58:59], v[66:67]
	v_pk_mul_f32 v[60:61], v[60:61], v[68:69]
	global_store_dwordx4 v[64:65], v[58:61], off offset:-4096 nt
	s_nop 1
	v_mov_b64_e32 v[58:59], v[124:125]
	v_mov_b64_e32 v[60:61], v[126:127]
	v_lshlrev_b32_e32 v68, 16, v104
	v_and_b32_e32 v69, 0xffff0000, v104
	v_add_co_u32_e32 v66, vcc, s18, v36
	v_pk_mul_f32 v[68:69], v[62:63], v[68:69] op_sel_hi:[0,1]
	s_nop 0
	v_addc_co_u32_e32 v67, vcc, 0, v37, vcc
	s_nop 0
	v_pk_mul_f32 v[58:59], v[58:59], v[68:69]
	v_pk_mul_f32 v[60:61], v[60:61], v[70:71]
	global_store_dwordx4 v[66:67], v[58:61], off offset:1024 nt
	s_nop 1
	v_mov_b64_e32 v[58:59], v[128:129]
	v_mov_b64_e32 v[60:61], v[130:131]
	v_lshlrev_b32_e32 v68, 16, v106
	v_and_b32_e32 v69, 0xffff0000, v106
	v_lshlrev_b32_e32 v70, 16, v107
	v_and_b32_e32 v71, 0xffff0000, v107
	v_pk_mul_f32 v[70:71], v[62:63], v[70:71] op_sel_hi:[0,1]
	v_pk_mul_f32 v[68:69], v[62:63], v[68:69] op_sel_hi:[0,1]
	s_nop 0
	v_pk_mul_f32 v[58:59], v[58:59], v[68:69]
	v_pk_mul_f32 v[60:61], v[60:61], v[70:71]
	global_store_dwordx4 v[66:67], v[58:61], off offset:2048 nt
	s_nop 1
	v_mov_b64_e32 v[58:59], v[132:133]
	v_mov_b64_e32 v[60:61], v[134:135]
	v_lshlrev_b32_e32 v68, 16, v108
	v_and_b32_e32 v69, 0xffff0000, v108
	v_lshlrev_b32_e32 v70, 16, v109
	v_and_b32_e32 v71, 0xffff0000, v109
	v_pk_mul_f32 v[70:71], v[62:63], v[70:71] op_sel_hi:[0,1]
	v_pk_mul_f32 v[62:63], v[62:63], v[68:69] op_sel_hi:[0,1]
	v_mov_b32_e32 v68, v28
	v_mov_b32_e32 v69, v20
	v_mov_b32_e32 v20, v29
	v_mov_b32_e32 v28, v30
	v_mov_b32_e32 v29, v22
	v_mov_b32_e32 v22, v31
	v_pk_add_f32 v[20:21], v[68:69], v[20:21]
	v_pk_add_f32 v[22:23], v[28:29], v[22:23]
	s_nop 0
	v_pk_mul_f32 v[58:59], v[58:59], v[62:63]
	v_pk_mul_f32 v[60:61], v[60:61], v[70:71]
	global_store_dwordx4 v[66:67], v[58:61], off offset:3072 nt
	s_nop 1
	v_mov_b64_e32 v[58:59], v[120:121]
	v_mov_b64_e32 v[60:61], v[122:123]
	v_mov_b32_e32 v62, v4
	v_mov_b32_e32 v4, v6
	v_mov_b32_e32 v6, v0
	v_mov_b32_e32 v0, v2
	v_mov_b32_e32 v63, v24
	v_mov_b32_e32 v24, v5
	v_mov_b32_e32 v5, v26
	v_mov_b32_e32 v26, v7
	v_mov_b32_e32 v7, v12
	v_mov_b32_e32 v12, v1
	v_mov_b32_e32 v1, v14
	v_mov_b32_e32 v14, v3
	v_mov_b32_e32 v2, v16
	v_mov_b32_e32 v3, v8
	v_mov_b32_e32 v8, v17
	v_mov_b32_e32 v16, v18
	v_mov_b32_e32 v17, v10
	v_mov_b32_e32 v10, v19
	v_pk_add_f32 v[24:25], v[62:63], v[24:25]
	v_pk_add_f32 v[4:5], v[4:5], v[26:27]
	v_pk_add_f32 v[6:7], v[6:7], v[12:13]
	v_pk_add_f32 v[0:1], v[0:1], v[14:15]
	v_pk_add_f32 v[2:3], v[2:3], v[8:9]
	v_pk_add_f32 v[8:9], v[16:17], v[10:11]
	v_pk_add_f32 v[4:5], v[24:25], v[4:5]
	v_pk_add_f32 v[20:21], v[20:21], v[22:23]
	v_pk_add_f32 v[0:1], v[6:7], v[0:1]
	v_pk_add_f32 v[2:3], v[2:3], v[8:9]
	v_pk_add_f32 v[4:5], v[4:5], v[20:21]
	v_pk_add_f32 v[0:1], v[0:1], v[2:3]
	v_mov_b32_e32 v7, v4
	v_mov_b32_e32 v6, v0
	v_mov_b32_e32 v4, v1
	v_pk_add_f32 v[0:1], v[6:7], v[4:5]
	v_lshlrev_b32_e32 v66, 16, v56
	v_pk_fma_f32 v[4:5], v[0:1], s[14:15], v[40:41] op_sel_hi:[1,0,0]
	v_and_b32_e32 v67, 0xffff0000, v56
	v_mul_f32_e32 v0, 0x4b800000, v5
	v_cmp_gt_f32_e32 vcc, s3, v5
	v_lshlrev_b32_e32 v56, 16, v57
	v_and_b32_e32 v57, 0xffff0000, v57
	v_cndmask_b32_e32 v0, v5, v0, vcc
	v_rsq_f32_e32 v0, v0
	v_lshlrev_b32_e32 v8, 16, v54
	v_and_b32_e32 v9, 0xffff0000, v54
	v_lshlrev_b32_e32 v10, 16, v55
	v_mul_f32_e32 v1, 0x45800000, v0
	v_cndmask_b32_e32 v6, v0, v1, vcc
	v_pk_mul_f32 v[2:3], v[6:7], v[56:57] op_sel_hi:[0,1]
	v_pk_mul_f32 v[0:1], v[6:7], v[66:67] op_sel_hi:[0,1]
	v_and_b32_e32 v11, 0xffff0000, v55
	v_pk_mul_f32 v[10:11], v[6:7], v[10:11] op_sel_hi:[0,1]
	v_pk_mul_f32 v[8:9], v[6:7], v[8:9] op_sel_hi:[0,1]
	v_mul_f32_e32 v5, 0x4b800000, v4
	s_nop 0
	v_pk_mul_f32 v[0:1], v[58:59], v[0:1]
	v_pk_mul_f32 v[2:3], v[60:61], v[2:3]
	global_store_dwordx4 v[64:65], v[0:3], off nt
	s_nop 1
	v_mov_b64_e32 v[0:1], v[124:125]
	v_mov_b64_e32 v[2:3], v[126:127]
	s_nop 0
	v_pk_mul_f32 v[0:1], v[0:1], v[8:9]
	v_pk_mul_f32 v[2:3], v[2:3], v[10:11]
	global_store_dwordx4 v[64:65], v[0:3], off offset:1024 nt
	s_nop 1
	v_mov_b64_e32 v[0:1], v[128:129]
	v_mov_b64_e32 v[2:3], v[130:131]
	v_lshlrev_b32_e32 v8, 16, v52
	v_and_b32_e32 v9, 0xffff0000, v52
	v_lshlrev_b32_e32 v10, 16, v53
	v_and_b32_e32 v11, 0xffff0000, v53
	v_pk_mul_f32 v[10:11], v[6:7], v[10:11] op_sel_hi:[0,1]
	v_pk_mul_f32 v[8:9], v[6:7], v[8:9] op_sel_hi:[0,1]
	s_nop 0
	v_pk_mul_f32 v[0:1], v[0:1], v[8:9]
	v_pk_mul_f32 v[2:3], v[2:3], v[10:11]
	global_store_dwordx4 v[64:65], v[0:3], off offset:2048 nt
	s_nop 1
	v_mov_b64_e32 v[0:1], v[132:133]
	v_mov_b64_e32 v[2:3], v[134:135]
	v_lshlrev_b32_e32 v8, 16, v50
	v_and_b32_e32 v9, 0xffff0000, v50
	v_lshlrev_b32_e32 v10, 16, v51
	v_and_b32_e32 v11, 0xffff0000, v51
	v_pk_mul_f32 v[10:11], v[6:7], v[10:11] op_sel_hi:[0,1]
	v_pk_mul_f32 v[6:7], v[6:7], v[8:9] op_sel_hi:[0,1]
	v_lshlrev_b32_e32 v8, 16, v48
	v_and_b32_e32 v9, 0xffff0000, v48
	s_nop 0
	v_pk_mul_f32 v[0:1], v[0:1], v[6:7]
	v_pk_mul_f32 v[2:3], v[2:3], v[10:11]
	global_store_dwordx4 v[64:65], v[0:3], off offset:3072 nt
	s_nop 1
	v_mov_b64_e32 v[0:1], v[120:121]
	v_mov_b64_e32 v[2:3], v[122:123]
	v_add_co_u32_e32 v6, vcc, s19, v36
	v_lshlrev_b32_e32 v10, 16, v49
	s_nop 0
	v_addc_co_u32_e32 v7, vcc, 0, v37, vcc
	v_cmp_gt_f32_e32 vcc, s3, v4
	v_and_b32_e32 v11, 0xffff0000, v49
	v_lshl_add_u64 v[36:37], v[36:37], 0, s[6:7]
	v_cndmask_b32_e32 v4, v4, v5, vcc
	v_rsq_f32_e32 v4, v4
	s_nop 0
	v_mul_f32_e32 v5, 0x45800000, v4
	v_cndmask_b32_e32 v4, v4, v5, vcc
	v_pk_mul_f32 v[10:11], v[4:5], v[10:11] op_sel_hi:[0,1]
	v_pk_mul_f32 v[8:9], v[4:5], v[8:9] op_sel_hi:[0,1]
	s_nop 0
	v_pk_mul_f32 v[0:1], v[0:1], v[8:9]
	v_pk_mul_f32 v[2:3], v[2:3], v[10:11]
	global_store_dwordx4 v[6:7], v[0:3], off nt
	s_nop 1
	v_mov_b64_e32 v[0:1], v[124:125]
	v_mov_b64_e32 v[2:3], v[126:127]
	v_lshlrev_b32_e32 v8, 16, v46
	v_and_b32_e32 v9, 0xffff0000, v46
	v_lshlrev_b32_e32 v10, 16, v47
	v_and_b32_e32 v11, 0xffff0000, v47
	v_pk_mul_f32 v[10:11], v[4:5], v[10:11] op_sel_hi:[0,1]
	v_pk_mul_f32 v[8:9], v[4:5], v[8:9] op_sel_hi:[0,1]
	s_nop 0
	v_pk_mul_f32 v[0:1], v[0:1], v[8:9]
	v_pk_mul_f32 v[2:3], v[2:3], v[10:11]
	global_store_dwordx4 v[6:7], v[0:3], off offset:1024 nt
	s_nop 1
	v_mov_b64_e32 v[0:1], v[128:129]
	v_mov_b64_e32 v[2:3], v[130:131]
	v_lshlrev_b32_e32 v8, 16, v44
	v_and_b32_e32 v9, 0xffff0000, v44
	v_lshlrev_b32_e32 v10, 16, v45
	v_and_b32_e32 v11, 0xffff0000, v45
	v_pk_mul_f32 v[10:11], v[4:5], v[10:11] op_sel_hi:[0,1]
	v_pk_mul_f32 v[8:9], v[4:5], v[8:9] op_sel_hi:[0,1]
	s_nop 0
	v_pk_mul_f32 v[0:1], v[0:1], v[8:9]
	v_pk_mul_f32 v[2:3], v[2:3], v[10:11]
	global_store_dwordx4 v[6:7], v[0:3], off offset:2048 nt
	s_nop 1
	v_mov_b64_e32 v[0:1], v[132:133]
	v_mov_b64_e32 v[2:3], v[134:135]
	v_lshlrev_b32_e32 v8, 16, v42
	v_and_b32_e32 v9, 0xffff0000, v42
	v_lshlrev_b32_e32 v10, 16, v43
	v_and_b32_e32 v11, 0xffff0000, v43
	v_pk_mul_f32 v[10:11], v[4:5], v[10:11] op_sel_hi:[0,1]
	v_pk_mul_f32 v[4:5], v[4:5], v[8:9] op_sel_hi:[0,1]
	s_nop 0
	v_pk_mul_f32 v[0:1], v[0:1], v[4:5]
	v_pk_mul_f32 v[2:3], v[2:3], v[10:11]
	global_store_dwordx4 v[6:7], v[0:3], off offset:3072 nt
	s_cbranch_scc1 .LBB0_1340
